# V-transpose loop: loop-top wait leaves the previous block's 4 stores outstanding (vmcnt(4)) instead of draining them
# baseline (speedup 1.0000x reference)
.Lvt_d_a:
	s_mul_i32 s5, s5, 0x1c00
	s_lshl_b32 s3, s3, 7
	s_add_i32 s5, s5, s3
	s_add_i32 s5, s5, 0xc00
	s_add_u32 s40, s70, s5
	s_addc_u32 s41, s71, 0
	s_add_u32 s42, s38, s6
	s_addc_u32 s43, s39, 0
	global_load_dwordx4 v[26:29], v54, s[40:41]
	global_load_dwordx4 v[30:33], v54, s[40:41] offset:16
	global_load_dwordx4 v[44:47], v54, s[40:41] offset:32
	global_load_dwordx4 v[48:51], v54, s[40:41] offset:48
	s_waitcnt vmcnt(0)
	s_branch .Lvt_body
.Lvt_loop:
	s_waitcnt vmcnt(4)
.Lvt_body:
	ds_write_b128 v56, v[26:29]
	ds_write_b128 v56, v[30:33] offset:16
	ds_write_b128 v56, v[44:47] offset:32
	ds_write_b128 v56, v[48:51] offset:48
	s_mov_b32 s44, s42
	s_mov_b32 s45, s43
	s_add_i32 s35, s35, s36
	s_cmp_ge_u32 s35, 0x2200
	s_cbranch_scc1 .Lvt_nonext
	s_cmp_lt_u32 s35, 0x2000
	s_cbranch_scc0 .Lvt_c_b
	s_lshr_b32 s2, s35, 10
	s_bfe_u32 s3, s35, 0x30007
	s_and_b32 s4, s35, 127
	s_lshl_b32 s5, s2, 12
	s_lshl_b32 s6, s4, 5
	s_add_i32 s5, s5, s6
	s_lshl_b32 s6, s2, 3
	s_add_i32 s6, s6, s3
	s_lshl_b32 s6, s6, 19
	s_lshl_b32 s7, s4, 12
	s_add_i32 s6, s6, s7
	s_branch .Lvt_d_b
